# NSA unit prologue de-serialisation: compressed-KV ready flag loaded speculatively at unit entry (overlaps query DMA), ring wait for compressed tiles moved below the query-fragment LDS reads
# baseline (speedup 1.0000x reference)
; DI void wait_count(unsigned* ctr, unsigned target) {
;   if (threadIdx.x == 0) {
;     unsigned sp = 0;
;     while (__hip_atomic_load(ctr, __ATOMIC_RELAXED, __HIP_MEMORY_SCOPE_AGENT) < target) { __builtin_amdgcn_s_sleep(2); if (++sp > (1u << 24)) break; }
;     __builtin_amdgcn_fence(__ATOMIC_ACQUIRE, "agent");
;     asm volatile("s_waitcnt vmcnt(0)" ::: "memory");
;   }
;   __syncthreads();
; }
; DI void nsa_unit(const Params& p, int b, int g, int qt, char* smem) {
;   const int wid = __builtin_amdgcn_readfirstlane(threadIdx.x >> 6);
;   int tid_ = threadIdx.x; asm volatile("" : "+v"(tid_)); const int tid = tid_, lane = tid & 63, l31 = lane & 31, h = lane >> 5;
;   const int tl = 8 * wid + (l31 >> 2), rr = l31 & 3, head = 4 * g + rr;
;   const int t = 64 * qt + tl;
;   const unsigned row = (unsigned)(b * NT + t);
;   char* Zc = p.ws + WS_Z;
;   LAS unsigned char* lds = (LAS unsigned char*)smem;
;   const unsigned ldsw = (unsigned)wid * 1024u;
;   const char* KC = p.ws + WS_KC + (size_t)((b * 2 + g) * 128) * 256;
;   const char* VC = KC + (size_t)4096 * 256;
;   const unsigned cvo = dma_voff128(wid, lane, 256), zvo = dma_voff128(wid, lane, ZW * 2);
;   const char* Zb = Zc + (size_t)b * NT * ZW * 2;
;   const int cKs = ZC_KV + 512 + g * 128, cVs = ZC_KV + 768 + g * 128, cKw = ZC_KV + 1024 + g * 128, cVw = ZC_KV + 1280 + g * 128;
;   const int nwin = (qt >= 8) ? 9 : (qt + 1);
;   const int NTILE = 3 + qt + nwin;
;     ...
;   f16x8 qf[8];
;   LAS unsigned char* qst = lds + (unsigned)(2 + (wid >> 2)) * 32768u + (unsigned)(wid & 3) * 8192u;
;   {
;     const unsigned qsrc0 = ((unsigned)(b * NT + 64 * qt + 8 * wid) * (unsigned)ZW + (unsigned)(ZC_QN + 4 * g * 128)) * 2u;
;     const int hc = lane >> 4, jc = lane & 15;
; #pragma unroll
;     for (int i = 0; i < 8; ++i) {
;       const unsigned kq = (unsigned)(((i & 3) << 2) | hc);
;       glds16(Zc + (size_t)(qsrc0 + (unsigned)i * (unsigned)(ZW * 2) + (((unsigned)hc * 16u + ((unsigned)jc ^ kq)) << 4)), qst + i * 1024);
;     }
;   }
;   f32x4 rt[4];
;   { const float* rp = (const float*)(p.ws + WS_ROT) + (size_t)row * 96 + 16 * h;
; #pragma unroll
;     for (int i = 0; i < 4; ++i) rt[i] = *(const f32x4*)(rp + 4 * i); }
;   float g0, g1, g2;
;   { const float* gp = (const float*)(p.ws + WS_GATES) + (size_t)(row * 24u + head); g0 = gp[0]; g1 = gp[8]; g2 = gp[16]; }
;   wait_count((unsigned*)(p.ws + WS_CTR) + 64 + b, 2u);
.LBB0_533:
	s_and_b64 vcc, exec, s[0:1]
	s_cbranch_vccz .LBB0_342
	v_readfirstlane_b32 s0, v0
	s_lshr_b32 s40, s44, 1
	s_lshl_b64 s[98:99], s[40:41], 2
	v_readlane_b32 s100, v255, 28
	s_add_u32 s98, s100, s98
	v_readlane_b32 s100, v255, 29
	s_addc_u32 s99, s100, s99
	global_load_dword v246, v207, s[98:99] sc1
	s_lshr_b32 s12, s0, 6
	s_lshr_b32 s5, s0, 8
	s_lshl_b32 s0, s0, 7
	s_lshl_b32 s8, s62, 6
	s_lshl_b32 s4, s40, 11
	v_writelane_b32 v255, s5, 40
	s_lshl_b32 s5, s5, 15
	s_and_b32 s0, s0, 0x6000
	v_mov_b32_e32 v92, v0
	s_lshl_b32 s1, s12, 3
	v_writelane_b32 v255, s0, 41
	s_or_b32 s0, s5, s0
	s_add_i32 s5, s8, s4
	s_and_b32 s3, s44, 1
	s_add_i32 s5, s5, s1
	v_bfe_u32 v183, v92, 4, 2
	s_mulk_i32 s5, 0x1800
	s_lshl_b32 s6, s3, 9
	v_and_b32_e32 v2, 48, v92
	v_bitop3_b32 v184, v183, v92, 15 bitop3:0x78
	s_or_b32 s5, s5, s6
	v_or_b32_e32 v3, v184, v2
	s_add_i32 s9, s0, 0x10000
	s_lshl_b32 s72, s5, 1
	v_and_b32_e32 v93, 15, v92
	v_lshlrev_b32_e32 v3, 4, v3
	v_or_b32_e32 v4, s72, v3
	s_mov_b32 m0, s9
	v_bitop3_b32 v182, v183, v93, 4 bitop3:0x36
	global_load_lds_dwordx4 v4, s[70:71]
	v_or_b32_e32 v4, v182, v2
	v_lshlrev_b32_e32 v4, 4, v4
	v_or_b32_e32 v5, s72, v4
	v_or_b32_e32 v5, 0x3000, v5
	s_add_i32 m0, s0, 0x10400
	s_add_i32 s5, s72, 0x9000
	global_load_lds_dwordx4 v5, s[70:71]
	v_bitop3_b32 v5, v183, v93, 8 bitop3:0x36
	v_or_b32_e32 v5, v5, v2
	v_lshlrev_b32_e32 v5, 4, v5
	v_or_b32_e32 v6, s72, v5
	v_or_b32_e32 v6, 0x6000, v6
	s_add_i32 m0, s0, 0x10800
	v_bfe_u32 v104, v92, 2, 3
	global_load_lds_dwordx4 v6, s[70:71]
	v_bitop3_b32 v6, v183, v93, 12 bitop3:0x36
	v_or_b32_e32 v2, v6, v2
	v_lshlrev_b32_e32 v2, 4, v2
	v_or_b32_e32 v6, s5, v2
	s_add_i32 m0, s0, 0x10c00
	s_add_i32 s5, s72, 0xc000
	global_load_lds_dwordx4 v6, s[70:71]
	v_or_b32_e32 v3, s5, v3
	s_add_i32 m0, s0, 0x11000
	s_add_i32 s5, s72, 0xf000
	global_load_lds_dwordx4 v3, s[70:71]
	v_or_b32_e32 v3, s5, v4
	s_add_i32 m0, s0, 0x11400
	s_add_i32 s5, s72, 0x12000
	global_load_lds_dwordx4 v3, s[70:71]
	v_or_b32_e32 v3, s5, v5
	s_add_i32 m0, s0, 0x11800
	s_add_i32 s5, s72, 0x15000
	global_load_lds_dwordx4 v3, s[70:71]
	s_add_i32 m0, s0, 0x11c00
	v_or_b32_e32 v67, s1, v104
	v_readlane_b32 s0, v255, 13
	v_or_b32_e32 v2, s5, v2
	v_add_u32_e32 v68, s8, v67
	v_readlane_b32 s1, v255, 14
	global_load_lds_dwordx4 v2, s[70:71]
	v_add_u32_e32 v18, s4, v68
	v_mov_b64_e32 v[2:3], s[0:1]
	s_movk_i32 s0, 0x180
	v_bfe_u32 v185, v92, 5, 1
	v_mad_u64_u32 v[2:3], s[0:1], v18, s0, v[2:3]
	v_and_b32_e32 v1, 3, v92
	v_lshlrev_b32_e32 v206, 6, v185
	s_lshl_b32 s0, s3, 2
	v_mul_lo_u32 v18, v18, 24
	v_lshl_add_u64 v[14:15], v[2:3], 0, v[206:207]
	v_or3_b32 v206, v18, s0, v1
	v_readlane_b32 s0, v255, 11
	v_readlane_b32 s1, v255, 12
	global_load_dwordx4 v[2:5], v[14:15], off offset:48
	global_load_dwordx4 v[6:9], v[14:15], off offset:32
	global_load_dwordx4 v[10:13], v[14:15], off offset:16
	s_nop 0
	global_load_dwordx4 v[14:17], v[14:15], off
	v_lshl_add_u64 v[18:19], v[206:207], 2, s[0:1]
	global_load_dword v66, v[18:19], off
	global_load_dword v191, v[18:19], off offset:32
	global_load_dword v187, v[18:19], off offset:64
	s_and_saveexec_b64 s[0:1], s[10:11]
	s_cbranch_execz .LBB0_549
	s_lshl_b64 s[4:5], s[40:41], 2
	v_readlane_b32 s6, v255, 28
	s_add_u32 s4, s6, s4
	v_readlane_b32 s6, v255, 29
	s_addc_u32 s5, s6, s5
	s_mov_b32 s13, 0x1000000
	s_waitcnt vmcnt(15)
	s_mov_b64 s[6:7], -1
	v_cmp_lt_u32_e32 vcc, 1, v246
	s_cbranch_vccnz .LBB0_537
	s_branch .LBB0_538

; #define LAS __attribute__((address_space(3)))
; DI void nsa_unit(const Params& p, int b, int g, int qt, char* smem) {
;     ...
;     ring_wait4(0);
;     {
;       const int tok_l = l31 >> 2;
;       const unsigned kq = (unsigned)(((tok_l & 3) << 2) | rr);
;       const unsigned qb = (unsigned)tok_l * 1024u + (unsigned)rr * 256u;
; #pragma unroll
;       for (int s = 0; s < 8; ++s) qf[s] = *(const LAS f16x8*)(qst + qb + ((((unsigned)(2 * s + h)) ^ kq) << 4));
.LBB0_551:
	v_mul_lo_u32 v18, v22, s93
	v_lshlrev_b32_e32 v19, 6, v92
	v_or3_b32 v206, v18, v21, v23
	v_lshrrev_b32_e32 v18, 2, v20
	v_and_b32_e32 v51, 0x1c0, v19
	v_bfe_u32 v19, v20, 2, 2
	v_bitop3_b32 v52, v18, v185, 3 bitop3:0x6c
	v_bitop3_b32 v53, v185, v19, 2 bitop3:0x36
	v_lshlrev_b32_e32 v18, 2, v19
	v_lshlrev_b32_e32 v19, 8, v1
	v_lshl_or_b32 v186, v104, 10, v19
	v_lshlrev_b32_e32 v50, 8, v20
	v_add_u32_e32 v19, s9, v186
	v_bitop3_b32 v20, v18, v185, v1 bitop3:0x36
	v_or_b32_e32 v95, 2, v185

; #define LAS __attribute__((address_space(3)))
; DI void ring_bar() { asm volatile("s_waitcnt lgkmcnt(0)" ::: "memory"); __builtin_amdgcn_s_barrier(); asm volatile("" ::: "memory"); }
; DI void nsa_unit(const Params& p, int b, int g, int qt, char* smem) {
;     ...
;       const int tok_l = l31 >> 2;
;       const unsigned kq = (unsigned)(((tok_l & 3) << 2) | rr);
;       const unsigned qb = (unsigned)tok_l * 1024u + (unsigned)rr * 256u;
; #pragma unroll
;       for (int s = 0; s < 8; ++s) qf[s] = *(const LAS f16x8*)(qst + qb + ((((unsigned)(2 * s + h)) ^ kq) << 4));
;       asm volatile("s_waitcnt lgkmcnt(0)" ::: "memory");
;     }
;     ring_bar();
;     NSA_ISSUE(2);
;     {
; #pragma unroll
;       for (int e = 0; e < 8; ++e) {
;         const float cs = rt[e >> 1][2 * (e & 1)], sn = rt[e >> 1][2 * (e & 1) + 1];
;         const float x1 = (float)qf[0][e], x2 = (float)qf[1][e];
;         qf[0][e] = (f16)((x1 * cs - x2 * sn) * QSCALE); qf[1][e] = (f16)((x1 * sn + x2 * cs) * QSCALE);
;       }
	v_lshl_add_u32 v20, v20, 4, v19
	ds_read_b128 v[26:29], v20
	v_bitop3_b32 v20, v18, v95, v1 bitop3:0x36
	v_lshl_add_u32 v20, v20, 4, v19
	ds_read_b128 v[30:33], v20
	v_or_b32_e32 v20, 4, v185
	v_bitop3_b32 v20, v18, v20, v1 bitop3:0x36
	v_lshl_add_u32 v20, v20, 4, v19
	s_lshl_b32 s75, s3, 7
	ds_read_b128 v[34:37], v20
	v_or_b32_e32 v20, 6, v185
	s_mul_i32 s1, s40, 0x1800000
	s_or_b32 s78, s75, 0x700
	s_or_b32 s79, s75, 0x900
	s_or_b32 s63, s75, 0x600
	v_bitop3_b32 v20, v18, v20, v1 bitop3:0x36
	s_mul_hi_u32 s0, s40, 0x1800000
	s_add_u32 s61, s70, s1
	v_lshl_add_u32 v20, v20, 4, v19
	s_addc_u32 s3, s71, s0
	ds_read_b128 v[38:41], v20
	v_or_b32_e32 v20, 8, v185
	s_movk_i32 s0, 0x1800
	v_bitop3_b32 v20, v18, v20, v1 bitop3:0x36
	v_and_or_b32 v50, v50, s0, v51
	s_lshl_b32 s0, s62, 7
	v_lshl_add_u32 v20, v20, 4, v19
	s_or_b32 s0, s0, 64
	s_bitset1_b32 s75, 11
	ds_read_b128 v[42:45], v20
	v_or_b32_e32 v20, 10, v185
	s_ashr_i32 s1, s0, 31
	v_bitop3_b32 v20, v18, v20, v1 bitop3:0x36
	s_cmp_gt_i32 s62, -1
	v_lshl_add_u32 v20, v20, 4, v19
	s_cselect_b32 s0, s8, s0
	s_cselect_b32 s1, 0, s1
	ds_read_b128 v[46:49], v20
	v_or_b32_e32 v20, 12, v185
	s_mulk_i32 s1, 0x3000
	s_mul_hi_u32 s8, s0, 0x3000
	v_bitop3_b32 v20, v18, v20, v1 bitop3:0x36
	s_cselect_b32 s6, s63, s75
	s_cselect_b32 s7, s78, s79
	s_add_i32 s8, s8, s1
	s_mulk_i32 s0, 0x3000
	v_lshl_add_u32 v20, v20, 4, v19
	s_add_u32 s9, s61, s0
	ds_read_b128 v[22:25], v20
	v_or_b32_e32 v20, 14, v185
	s_addc_u32 s8, s3, s8
	s_lshl_b32 s0, s6, 1
	v_bitop3_b32 v18, v18, v20, v1 bitop3:0x36
	s_add_u32 s0, s9, s0
	v_lshl_add_u32 v18, v18, 4, v19
	s_addc_u32 s1, s8, 0
	s_lshl_b32 s6, s7, 1
	ds_read_b128 v[18:21], v18
	s_waitcnt lgkmcnt(0)
	s_add_u32 s6, s9, s6
	v_lshl_or_b32 v190, v52, 4, v50
	v_lshl_or_b32 v189, v53, 4, v50
	s_waitcnt lgkmcnt(0)
	s_waitcnt vmcnt(0)
	s_barrier
	s_addc_u32 s7, s8, 0
	v_lshl_add_u64 v[50:51], s[0:1], 0, v[206:207]
	s_add_i32 m0, s60, 0x10000
	v_lshl_add_u64 v[50:51], v[50:51], 0, s[86:87]
	global_load_lds_dwordx4 v206, s[0:1]
	s_add_i32 m0, s60, 0x12000
	s_waitcnt lgkmcnt(0)
	v_cvt_f32_f16_e32 v52, v30
	global_load_lds_dwordx4 v[50:51], off
	v_lshl_add_u64 v[50:51], s[6:7], 0, v[206:207]
	s_add_i32 m0, s60, 0x14000
	v_lshl_add_u64 v[50:51], v[50:51], 0, s[86:87]
	global_load_lds_dwordx4 v206, s[6:7]
	s_add_i32 m0, s60, 0x16000
	v_cvt_f32_f16_sdwa v53, v30 dst_sel:DWORD dst_unused:UNUSED_PAD src0_sel:WORD_1
	global_load_lds_dwordx4 v[50:51], off
	v_cvt_f32_f16_e32 v50, v26
	v_cvt_f32_f16_sdwa v51, v26 dst_sel:DWORD dst_unused:UNUSED_PAD src0_sel:WORD_1
	v_mov_b32_e32 v55, v16
	v_mov_b32_e32 v16, v15
	v_mov_b32_e32 v54, v14
	v_pk_mul_f32 v[14:15], v[16:17], v[52:53]
	v_mov_b32_e32 v26, v10
	v_pk_fma_f32 v[14:15], v[54:55], v[50:51], v[14:15] neg_lo:[0,0,1] neg_hi:[0,0,1]
	s_andn2_b64 vcc, exec, s[4:5]
	v_pk_mul_f32 v[14:15], v[14:15], s[56:57] op_sel_hi:[1,0]
	v_mov_b32_e32 v56, 0
	v_cvt_pk_f16_f32 v150, v14, v15
	v_pk_mul_f32 v[14:15], v[54:55], v[52:53]
	v_mov_b32_e32 v52, 0
	v_pk_fma_f32 v[14:15], v[16:17], v[50:51], v[14:15]
	v_cvt_f32_f16_e32 v16, v31
	v_pk_mul_f32 v[14:15], v[14:15], s[56:57] op_sel_hi:[1,0]
	v_cvt_f32_f16_sdwa v17, v31 dst_sel:DWORD dst_unused:UNUSED_PAD src0_sel:WORD_1
	v_cvt_pk_f16_f32 v158, v14, v15
	v_cvt_f32_f16_e32 v14, v27
	v_cvt_f32_f16_sdwa v15, v27 dst_sel:DWORD dst_unused:UNUSED_PAD src0_sel:WORD_1
	v_mov_b32_e32 v27, v12
	v_mov_b32_e32 v12, v11
	v_pk_mul_f32 v[10:11], v[12:13], v[16:17]
	v_cvt_f32_f16_sdwa v51, v20 dst_sel:DWORD dst_unused:UNUSED_PAD src0_sel:WORD_1
	v_pk_fma_f32 v[10:11], v[26:27], v[14:15], v[10:11] neg_lo:[0,0,1] neg_hi:[0,0,1]
	v_mov_b32_e32 v53, 0
	v_pk_mul_f32 v[10:11], v[10:11], s[56:57] op_sel_hi:[1,0]
	v_mov_b32_e32 v54, 0
	v_cvt_pk_f16_f32 v151, v10, v11
	v_pk_mul_f32 v[10:11], v[26:27], v[16:17]
	v_mov_b32_e32 v55, 0
	v_pk_fma_f32 v[10:11], v[12:13], v[14:15], v[10:11]
	v_cvt_f32_f16_e32 v12, v32
	v_pk_mul_f32 v[10:11], v[10:11], s[56:57] op_sel_hi:[1,0]
	v_cvt_f32_f16_sdwa v13, v32 dst_sel:DWORD dst_unused:UNUSED_PAD src0_sel:WORD_1
	v_cvt_pk_f16_f32 v159, v10, v11
	v_cvt_f32_f16_e32 v10, v28
	v_cvt_f32_f16_sdwa v11, v28 dst_sel:DWORD dst_unused:UNUSED_PAD src0_sel:WORD_1
	v_mov_b32_e32 v15, v8
	v_mov_b32_e32 v8, v7
	v_mov_b32_e32 v14, v6
	v_pk_mul_f32 v[6:7], v[8:9], v[12:13]
	v_mov_b32_e32 v57, 0
	v_pk_fma_f32 v[6:7], v[14:15], v[10:11], v[6:7] neg_lo:[0,0,1] neg_hi:[0,0,1]
	v_mov_b32_e32 v58, 0
	v_pk_mul_f32 v[6:7], v[6:7], s[56:57] op_sel_hi:[1,0]
	v_mov_b32_e32 v59, 0
	v_cvt_pk_f16_f32 v152, v6, v7
	v_pk_mul_f32 v[6:7], v[14:15], v[12:13]
	v_mov_b32_e32 v60, 0
	v_pk_fma_f32 v[6:7], v[8:9], v[10:11], v[6:7]
	v_cvt_f32_f16_e32 v8, v33
	v_pk_mul_f32 v[6:7], v[6:7], s[56:57] op_sel_hi:[1,0]
	v_cvt_f32_f16_sdwa v9, v33 dst_sel:DWORD dst_unused:UNUSED_PAD src0_sel:WORD_1
	v_cvt_pk_f16_f32 v160, v6, v7
	v_cvt_f32_f16_e32 v6, v29
	v_cvt_f32_f16_sdwa v7, v29 dst_sel:DWORD dst_unused:UNUSED_PAD src0_sel:WORD_1
	v_mov_b32_e32 v11, v4
	v_mov_b32_e32 v4, v3
	v_mov_b32_e32 v10, v2
	v_pk_mul_f32 v[2:3], v[4:5], v[8:9]
	ds_read_b128 v[26:29], v189 offset:8192
	v_pk_fma_f32 v[2:3], v[10:11], v[6:7], v[2:3] neg_lo:[0,0,1] neg_hi:[0,0,1]
	v_mov_b32_e32 v61, 0
	v_pk_mul_f32 v[2:3], v[2:3], s[56:57] op_sel_hi:[1,0]
	v_mov_b32_e32 v62, 0
	v_cvt_pk_f16_f32 v153, v2, v3
	v_pk_mul_f32 v[2:3], v[10:11], v[8:9]
	v_cvt_f32_f16_e32 v8, v34
	v_cvt_f32_f16_sdwa v9, v34 dst_sel:DWORD dst_unused:UNUSED_PAD src0_sel:WORD_1
	v_pk_fma_f32 v[2:3], v[4:5], v[6:7], v[2:3]
	v_cvt_f32_f16_e32 v4, v35
	v_cvt_f32_f16_sdwa v5, v35 dst_sel:DWORD dst_unused:UNUSED_PAD src0_sel:WORD_1
	v_pk_mul_f32 v[2:3], v[2:3], s[56:57] op_sel_hi:[1,0]
; #define MFMA(a, b, c) __builtin_amdgcn_mfma_f32_32x32x16_f16((a), (b), (c), 0, 0, 0)
; #define QK_LD(dst, s0) do { dst[0] = *(const f16x8*)(Kst + kbe + 512 * ((s0) >> 1)); dst[1] = *(const f16x8*)(Kst + kbe + 512 * ((s0) >> 1) + 8192); \
;     dst[2] = *(const f16x8*)(Kst + kbo + 512 * ((s0) >> 1)); dst[3] = *(const f16x8*)(Kst + kbo + 512 * ((s0) >> 1) + 8192); } while (0)
; #define QK_LD(dst, s0) do { dst[0] = *(const f16x8*)(Kst + kbe + 512 * ((s0) >> 1)); dst[1] = *(const f16x8*)(Kst + kbe + 512 * ((s0) >> 1) + 8192); \
;     dst[2] = *(const f16x8*)(Kst + kbo + 512 * ((s0) >> 1)); dst[3] = *(const f16x8*)(Kst + kbo + 512 * ((s0) >> 1) + 8192); } while (0)
; DI void qk128(f32x16& p0, f32x16& p1, const char* Kst, const f16x8 (&qf)[8], unsigned kbe, unsigned kbo) {
;   const f32x16 zero = {0.f, 0.f, 0.f, 0.f, 0.f, 0.f, 0.f, 0.f, 0.f, 0.f, 0.f, 0.f, 0.f, 0.f, 0.f, 0.f};
;   f16x8 ka[4], kb[4];
;     ...
;   QK_LD(ka, 0);
;   QK_LD(kb, 2);
;   p0 = MFMA(ka[0], qf[0], zero); p1 = MFMA(ka[1], qf[0], zero); p0 = MFMA(ka[2], qf[1], p0); p1 = MFMA(ka[3], qf[1], p1);
;   QK_LD(ka, 4);
;   p0 = MFMA(kb[0], qf[2], p0); p1 = MFMA(kb[1], qf[2], p1); p0 = MFMA(kb[2], qf[3], p0); p1 = MFMA(kb[3], qf[3], p1);
;   QK_LD(kb, 6);
;   p0 = MFMA(ka[0], qf[4], p0); p1 = MFMA(ka[1], qf[4], p1); p0 = MFMA(ka[2], qf[5], p0); p1 = MFMA(ka[3], qf[5], p1);
;   p0 = MFMA(kb[0], qf[6], p0); p1 = MFMA(kb[1], qf[6], p1); p0 = MFMA(kb[2], qf[7], p0); p1 = MFMA(kb[3], qf[7], p1);
; DI void nsa_unit(const Params& p, int b, int g, int qt, char* smem) {
;     ...
; #pragma unroll
;       for (int s = 2; s < 8; ++s)
; #pragma unroll
;         for (int e = 0; e < 8; ++e) qf[s][e] = (f16)((float)qf[s][e] * QSCALE);
;     }
;     f32x16 c0, c1, c2, c3;
;     qk128(c0, c1, smem, qf, kbe, kbo);
;     if (qt >= 16) qk128(c2, c3, smem + 32768, qf, kbe, kbo);
;     else {
; #pragma unroll
;       for (int r = 0; r < 16; ++r) { c2[r] = 0.f; c3[r] = 0.f; }
;     }
	v_cvt_f32_f16_e32 v6, v36
	v_cvt_pk_f16_f32 v161, v2, v3
	v_pk_mul_f32 v[2:3], v[8:9], s[56:57] op_sel_hi:[1,0]
	v_cvt_f32_f16_sdwa v7, v36 dst_sel:DWORD dst_unused:UNUSED_PAD src0_sel:WORD_1
	v_cvt_pk_f16_f32 v142, v2, v3
	v_pk_mul_f32 v[2:3], v[4:5], s[56:57] op_sel_hi:[1,0]
	v_cvt_f32_f16_e32 v4, v37
	v_cvt_f32_f16_sdwa v5, v37 dst_sel:DWORD dst_unused:UNUSED_PAD src0_sel:WORD_1
	v_cvt_pk_f16_f32 v143, v2, v3
	v_pk_mul_f32 v[2:3], v[6:7], s[56:57] op_sel_hi:[1,0]
	v_cvt_f32_f16_e32 v6, v38
	v_cvt_f32_f16_sdwa v7, v38 dst_sel:DWORD dst_unused:UNUSED_PAD src0_sel:WORD_1
	v_cvt_pk_f16_f32 v144, v2, v3
	v_pk_mul_f32 v[2:3], v[4:5], s[56:57] op_sel_hi:[1,0]
	v_cvt_f32_f16_e32 v4, v39
	v_cvt_f32_f16_sdwa v5, v39 dst_sel:DWORD dst_unused:UNUSED_PAD src0_sel:WORD_1
	v_cvt_pk_f16_f32 v145, v2, v3
	v_pk_mul_f32 v[2:3], v[6:7], s[56:57] op_sel_hi:[1,0]
	v_cvt_f32_f16_e32 v6, v40
	v_cvt_f32_f16_sdwa v7, v40 dst_sel:DWORD dst_unused:UNUSED_PAD src0_sel:WORD_1
	v_cvt_pk_f16_f32 v154, v2, v3
	v_pk_mul_f32 v[2:3], v[4:5], s[56:57] op_sel_hi:[1,0]
	v_cvt_f32_f16_e32 v4, v41
	v_cvt_f32_f16_sdwa v5, v41 dst_sel:DWORD dst_unused:UNUSED_PAD src0_sel:WORD_1
	v_cvt_pk_f16_f32 v155, v2, v3
	v_pk_mul_f32 v[2:3], v[6:7], s[56:57] op_sel_hi:[1,0]
	v_cvt_f32_f16_e32 v6, v47
	v_cvt_pk_f16_f32 v156, v2, v3
	v_cvt_f32_f16_e32 v2, v42
	v_cvt_f32_f16_sdwa v3, v42 dst_sel:DWORD dst_unused:UNUSED_PAD src0_sel:WORD_1
	v_pk_mul_f32 v[4:5], v[4:5], s[56:57] op_sel_hi:[1,0]
	v_cvt_f32_f16_sdwa v7, v47 dst_sel:DWORD dst_unused:UNUSED_PAD src0_sel:WORD_1
	v_cvt_pk_f16_f32 v157, v4, v5
	v_cvt_f32_f16_e32 v4, v43
	v_cvt_f32_f16_sdwa v5, v43 dst_sel:DWORD dst_unused:UNUSED_PAD src0_sel:WORD_1
	v_pk_mul_f32 v[2:3], v[2:3], s[56:57] op_sel_hi:[1,0]
	v_cvt_f32_f16_e32 v8, v48
	v_cvt_pk_f16_f32 v138, v2, v3
	v_mul_f32_e32 v2, 0x3e0293ee, v4
	v_cvt_f32_f16_e32 v3, v44
	v_mul_f32_e32 v4, 0x3e0293ee, v5
	v_cvt_f32_f16_sdwa v5, v44 dst_sel:DWORD dst_unused:UNUSED_PAD src0_sel:WORD_1
	v_cvt_pk_f16_f32 v139, v2, v4
	v_mul_f32_e32 v2, 0x3e0293ee, v3
	v_cvt_f32_f16_e32 v3, v45
	v_mul_f32_e32 v4, 0x3e0293ee, v5
	v_cvt_pk_f16_f32 v140, v2, v4
	v_cvt_f32_f16_sdwa v2, v45 dst_sel:DWORD dst_unused:UNUSED_PAD src0_sel:WORD_1
	v_cvt_f32_f16_e32 v4, v46
	v_cvt_f32_f16_sdwa v5, v46 dst_sel:DWORD dst_unused:UNUSED_PAD src0_sel:WORD_1
	v_mul_f32_e32 v3, 0x3e0293ee, v3
	v_mul_f32_e32 v2, 0x3e0293ee, v2
	v_cvt_pk_f16_f32 v141, v3, v2
	v_mul_f32_e32 v30, 0x3e0293ee, v4
	v_mul_f32_e32 v31, 0x3e0293ee, v5
	ds_read_b128 v[2:5], v190 offset:8192
	v_cvt_f32_f16_sdwa v9, v48 dst_sel:DWORD dst_unused:UNUSED_PAD src0_sel:WORD_1
	v_cvt_f32_f16_e32 v38, v22
	v_cvt_f32_f16_sdwa v22, v22 dst_sel:DWORD dst_unused:UNUSED_PAD src0_sel:WORD_1
	v_cvt_f32_f16_e32 v39, v23
	v_cvt_f32_f16_sdwa v23, v23 dst_sel:DWORD dst_unused:UNUSED_PAD src0_sel:WORD_1
	v_mul_f32_e32 v32, 0x3e0293ee, v6
	v_mul_f32_e32 v33, 0x3e0293ee, v7
	v_mul_f32_e32 v34, 0x3e0293ee, v8
	v_mul_f32_e32 v35, 0x3e0293ee, v9
	v_cvt_f32_f16_e32 v40, v24
	v_mul_f32_e32 v41, 0x3e0293ee, v22
	v_mul_f32_e32 v42, 0x3e0293ee, v23
	v_cvt_f32_f16_sdwa v43, v24 dst_sel:DWORD dst_unused:UNUSED_PAD src0_sel:WORD_1
	v_cvt_f32_f16_e32 v44, v25
	v_cvt_f32_f16_sdwa v45, v25 dst_sel:DWORD dst_unused:UNUSED_PAD src0_sel:WORD_1
	ds_read_b128 v[22:25], v189 offset:8704
	s_waitcnt lgkmcnt(0)
	v_mfma_f32_32x32x16_f16 v[2:17], v[2:5], v[150:153], 0
	v_cvt_f32_f16_e32 v46, v18
	v_cvt_f32_f16_sdwa v18, v18 dst_sel:DWORD dst_unused:UNUSED_PAD src0_sel:WORD_1
	v_cvt_f32_f16_e32 v36, v49
	v_cvt_f32_f16_sdwa v37, v49 dst_sel:DWORD dst_unused:UNUSED_PAD src0_sel:WORD_1
	v_cvt_f32_f16_e32 v47, v19
	v_cvt_f32_f16_sdwa v19, v19 dst_sel:DWORD dst_unused:UNUSED_PAD src0_sel:WORD_1
	v_mul_f32_e32 v48, 0x3e0293ee, v18
	v_mfma_f32_32x32x16_f16 v[2:17], v[26:29], v[158:161], v[2:17]
	ds_read_b128 v[26:29], v190 offset:8704
	v_cvt_f32_f16_e32 v18, v20
	v_mul_f32_e32 v36, 0x3e0293ee, v36
	v_mul_f32_e32 v37, 0x3e0293ee, v37
	v_cvt_pk_f16_f32 v149, v36, v37
	v_cvt_pk_f16_f32 v148, v34, v35
	v_cvt_pk_f16_f32 v147, v32, v33
	s_waitcnt lgkmcnt(0)
	v_mfma_f32_32x32x16_f16 v[2:17], v[26:29], v[142:145], v[2:17]
	ds_read_b128 v[26:29], v190 offset:9216
	v_cvt_pk_f16_f32 v146, v30, v31
	v_mul_f32_e32 v49, 0x3e0293ee, v19
	v_mul_f32_e32 v50, 0x3e0293ee, v18
	v_mul_f32_e32 v38, 0x3e0293ee, v38
	v_mul_f32_e32 v39, 0x3e0293ee, v39
	v_mul_f32_e32 v40, 0x3e0293ee, v40
	v_mfma_f32_32x32x16_f16 v[2:17], v[22:25], v[154:157], v[2:17]
	ds_read_b128 v[22:25], v189 offset:9216
	v_mul_f32_e32 v43, 0x3e0293ee, v43
	v_mul_f32_e32 v44, 0x3e0293ee, v44
	v_mul_f32_e32 v45, 0x3e0293ee, v45
	v_cvt_pk_f16_f32 v133, v44, v45
	v_cvt_pk_f16_f32 v132, v40, v43
	v_cvt_pk_f16_f32 v131, v39, v42
	s_waitcnt lgkmcnt(0)
	v_mfma_f32_32x32x16_f16 v[2:17], v[26:29], v[138:141], v[2:17]
	v_cvt_pk_f16_f32 v130, v38, v41
	v_mul_f32_e32 v46, 0x3e0293ee, v46
	v_mul_f32_e32 v47, 0x3e0293ee, v47
	v_cvt_pk_f16_f32 v135, v47, v49
	v_cvt_pk_f16_f32 v134, v46, v48
	ds_read_b128 v[34:37], v189
	ds_read_b128 v[38:41], v189 offset:512
	v_mfma_f32_32x32x16_f16 v[2:17], v[22:25], v[146:149], v[2:17]
	v_cvt_f32_f16_e32 v22, v21
	v_cvt_f32_f16_sdwa v23, v21 dst_sel:DWORD dst_unused:UNUSED_PAD src0_sel:WORD_1
	ds_read_b128 v[18:21], v189 offset:9728
	ds_read_b128 v[26:29], v190 offset:9728
	v_mul_f32_e32 v24, 0x3e0293ee, v51
	v_mul_f32_e32 v22, 0x3e0293ee, v22
	v_mul_f32_e32 v23, 0x3e0293ee, v23
	s_waitcnt lgkmcnt(0)
	v_mfma_f32_32x32x16_f16 v[2:17], v[26:29], v[130:133], v[2:17]
	v_cvt_pk_f16_f32 v137, v22, v23
	v_cvt_pk_f16_f32 v136, v50, v24
	v_mov_b32_e32 v42, 0
	v_mov_b32_e32 v43, 0
	v_mov_b32_e32 v44, 0
	v_mov_b32_e32 v45, 0
	v_mov_b32_e32 v46, 0
	v_mfma_f32_32x32x16_f16 v[2:17], v[18:21], v[134:137], v[2:17]
	ds_read_b128 v[18:21], v190
	v_mov_b32_e32 v47, 0
	v_mov_b32_e32 v48, 0
	v_mov_b32_e32 v49, 0
	v_mov_b32_e32 v50, 0
	v_mov_b32_e32 v51, 0
	v_mov_b32_e32 v63, 0
	s_waitcnt lgkmcnt(0)
	v_mfma_f32_32x32x16_f16 v[18:33], v[18:21], v[150:153], 0
	v_mov_b32_e32 v64, 0
	v_mov_b32_e32 v65, 0
	v_mfma_f32_32x32x16_f16 v[18:33], v[34:37], v[158:161], v[18:33]
	ds_read_b128 v[34:37], v190 offset:512
	s_waitcnt lgkmcnt(0)
	v_mfma_f32_32x32x16_f16 v[18:33], v[34:37], v[142:145], v[18:33]
	ds_read_b128 v[34:37], v190 offset:1024
	v_mfma_f32_32x32x16_f16 v[18:33], v[38:41], v[154:157], v[18:33]
	v_mov_b32_e32 v38, 0
	v_mov_b32_e32 v39, 0
	v_mov_b32_e32 v40, 0
	v_mov_b32_e32 v41, 0
	s_waitcnt lgkmcnt(0)
	v_mfma_f32_32x32x16_f16 v[18:33], v[34:37], v[138:141], v[18:33]
	ds_read_b128 v[34:37], v189 offset:1024
	s_waitcnt lgkmcnt(0)
	v_mfma_f32_32x32x16_f16 v[18:33], v[34:37], v[146:149], v[18:33]
	ds_read_b128 v[34:37], v190 offset:1536
	s_waitcnt lgkmcnt(0)
	v_mfma_f32_32x32x16_f16 v[18:33], v[34:37], v[130:133], v[18:33]
	ds_read_b128 v[34:37], v189 offset:1536
	s_waitcnt lgkmcnt(0)
	v_mfma_f32_32x32x16_f16 v[18:33], v[34:37], v[134:137], v[18:33]
	v_cndmask_b32_e64 v35, 0, 1, s[4:5]
	v_mov_b32_e32 v34, 0
	v_cmp_ne_u32_e64 s[0:1], 1, v35
	v_mov_b32_e32 v35, 0
	v_mov_b32_e32 v36, 0
	v_mov_b32_e32 v37, 0
	s_cbranch_vccnz .LBB0_553
; #define MFMA(a, b, c) __builtin_amdgcn_mfma_f32_32x32x16_f16((a), (b), (c), 0, 0, 0)
; #define QK_LD(dst, s0) do { dst[0] = *(const f16x8*)(Kst + kbe + 512 * ((s0) >> 1)); dst[1] = *(const f16x8*)(Kst + kbe + 512 * ((s0) >> 1) + 8192); \
;     dst[2] = *(const f16x8*)(Kst + kbo + 512 * ((s0) >> 1)); dst[3] = *(const f16x8*)(Kst + kbo + 512 * ((s0) >> 1) + 8192); } while (0)
; #define QK_LD(dst, s0) do { dst[0] = *(const f16x8*)(Kst + kbe + 512 * ((s0) >> 1)); dst[1] = *(const f16x8*)(Kst + kbe + 512 * ((s0) >> 1) + 8192); \
;     dst[2] = *(const f16x8*)(Kst + kbo + 512 * ((s0) >> 1)); dst[3] = *(const f16x8*)(Kst + kbo + 512 * ((s0) >> 1) + 8192); } while (0)
; DI void qk128(f32x16& p0, f32x16& p1, const char* Kst, const f16x8 (&qf)[8], unsigned kbe, unsigned kbo) {
;   const f32x16 zero = {0.f, 0.f, 0.f, 0.f, 0.f, 0.f, 0.f, 0.f, 0.f, 0.f, 0.f, 0.f, 0.f, 0.f, 0.f, 0.f};
;   f16x8 ka[4], kb[4];
;     ...
;   QK_LD(ka, 0);
;   QK_LD(kb, 2);
;   p0 = MFMA(ka[0], qf[0], zero); p1 = MFMA(ka[1], qf[0], zero); p0 = MFMA(ka[2], qf[1], p0); p1 = MFMA(ka[3], qf[1], p1);
;   QK_LD(ka, 4);
;   p0 = MFMA(kb[0], qf[2], p0); p1 = MFMA(kb[1], qf[2], p1); p0 = MFMA(kb[2], qf[3], p0); p1 = MFMA(kb[3], qf[3], p1);
;   QK_LD(kb, 6);
;   p0 = MFMA(ka[0], qf[4], p0); p1 = MFMA(ka[1], qf[4], p1); p0 = MFMA(ka[2], qf[5], p0); p1 = MFMA(ka[3], qf[5], p1);
;   p0 = MFMA(kb[0], qf[6], p0); p1 = MFMA(kb[1], qf[6], p1); p0 = MFMA(kb[2], qf[7], p0); p1 = MFMA(kb[3], qf[7], p1);
	ds_read_b128 v[34:37], v190 offset:32768
	ds_read_b128 v[38:41], v190 offset:40960
	ds_read_b128 v[70:73], v189 offset:32768
	ds_read_b128 v[74:77], v189 offset:40960
	ds_read_b128 v[78:81], v190 offset:33280
	ds_read_b128 v[82:85], v190 offset:41472
	ds_read_b128 v[86:89], v189 offset:33280
	ds_read_b128 v[96:99], v189 offset:41472
	s_waitcnt lgkmcnt(0)
	v_mfma_f32_32x32x16_f16 v[50:65], v[34:37], v[150:153], 0
	v_mfma_f32_32x32x16_f16 v[34:49], v[38:41], v[150:153], 0
	v_mfma_f32_32x32x16_f16 v[50:65], v[70:73], v[158:161], v[50:65]
	v_mfma_f32_32x32x16_f16 v[34:49], v[74:77], v[158:161], v[34:49]
	ds_read_b128 v[70:73], v190 offset:33792
	ds_read_b128 v[74:77], v190 offset:41984
	ds_read_b128 v[100:103], v189 offset:33792
	ds_read_b128 v[106:109], v189 offset:41984
	v_mfma_f32_32x32x16_f16 v[50:65], v[78:81], v[142:145], v[50:65]
	v_mfma_f32_32x32x16_f16 v[34:49], v[82:85], v[142:145], v[34:49]
	v_mfma_f32_32x32x16_f16 v[50:65], v[86:89], v[154:157], v[50:65]
	v_mfma_f32_32x32x16_f16 v[34:49], v[96:99], v[154:157], v[34:49]
	ds_read_b128 v[78:81], v190 offset:34304
	ds_read_b128 v[82:85], v190 offset:42496
	ds_read_b128 v[86:89], v189 offset:34304
	ds_read_b128 v[96:99], v189 offset:42496
	s_waitcnt lgkmcnt(0)
	v_mfma_f32_32x32x16_f16 v[50:65], v[70:73], v[138:141], v[50:65]
	v_mfma_f32_32x32x16_f16 v[34:49], v[74:77], v[138:141], v[34:49]
	v_mfma_f32_32x32x16_f16 v[50:65], v[100:103], v[146:149], v[50:65]
	v_mfma_f32_32x32x16_f16 v[34:49], v[106:109], v[146:149], v[34:49]
	v_mfma_f32_32x32x16_f16 v[50:65], v[78:81], v[130:133], v[50:65]
	v_mfma_f32_32x32x16_f16 v[34:49], v[82:85], v[130:133], v[34:49]
	v_mfma_f32_32x32x16_f16 v[50:65], v[86:89], v[134:137], v[50:65]
	v_mfma_f32_32x32x16_f16 v[34:49], v[96:99], v[134:137], v[34:49]
